# S5 Kc lag-kernel table computed on f32 matrix cores (v_mfma_f32_16x16x4_f32, one wave per (group,dir,lag) tile) instead of a per-thread 64-step VALU loop
# speedup vs baseline: 1.0772x; 1.0100x over previous
; __device__ __forceinline__ const float* inp(int k) { const CAS cfptr* p = (const CAS cfptr*)__builtin_amdgcn_kernarg_segment_ptr(); asm volatile("" : "+s"(p)); return p[k]; }
; #define LANE_IDS() const int f_tid = tid_(); const int f_lane = f_tid & 63; const int f_gtid = blockIdx.x * (NWAVES * 64) + f_tid; (void)f_lane; (void)f_gtid
; __device__ __forceinline__ void p0b_tables(Frame& F, const Args& A, int t0) {
;     LANE_IDS();
;     const int tg = f_gtid - t0, tn = F.NGT - t0; if (tg < 0) return;
;     unsigned char* ws = F.ws;
;     const f32x2* apow = (const f32x2*)(ws + WS_APOW); const f32x2* bbar = (const f32x2*)(ws + WS_BBAR);
;     float* Kc = (float*)(ws + WS_KC); bf16* WBT = (bf16*)(ws + WS_WBT); bf16* TBT = (bf16*)(ws + WS_TBT);
;     const float* Cre = inp(16); const float* Cim = inp(17);
;     for (int i = tg; i < 64 * 2 * 16 * 256; i += tn) {
;         const int c = i & 15, cp = (i >> 4) & 15, k = (i >> 8) & 15, dir = (i >> 12) & 1, g = i >> 13;
;         const f32x2* ap = apow + ((g * 2 + dir) * 17 + k) * 64; const f32x2* bb = bbar + (size_t)((g * 2 + dir) * 64) * 16 + c;
;         const float* cr = Cre + ((size_t)(dir * 64 + g) * 16 + cp) * 64; const float* ci = Cim + ((size_t)(dir * 64 + g) * 16 + cp) * 64;
;         float s = 0.f;
;         for (int p = 0; p < 64; ++p) { const f32x2 a = ap[p], b = bb[p * 16]; const float xr = a.x * b.x - a.y * b.y, xi = a.x * b.y + a.y * b.x; s += cr[p] * xr - ci[p] * xi; }
;         Kc[i] = s;
;     }
.LBB0_289:
	s_andn2_b64 vcc, exec, s[10:11]
	s_cbranch_vccnz .LBB0_301
	s_sub_i32 s3, s2, s84
	v_mov_b32_e32 v0, v188
	s_nop 0
	v_lshl_add_u32 v14, s3, 9, v0
	v_cmp_lt_i32_e32 vcc, -1, v14
	s_and_saveexec_b64 s[4:5], vcc
	s_cbranch_execz .LBB0_300
	s_mov_b32 s3, 0x80000
	s_mov_b64 s[12:13], s[0:1]
	s_mov_b64 s[16:17], s[0:1]
	v_cmp_gt_u32_e32 vcc, s3, v14
	s_and_b64 exec, exec, vcc
	s_cbranch_execz .LBB0_300
	s_load_dwordx2 s[6:7], s[12:13], 0x80
	s_load_dwordx2 s[8:9], s[16:17], 0x88
	s_add_u32 s10, s14, 0x400000
	s_addc_u32 s11, s15, 0
	s_sub_i32 s3, s82, s84
	v_and_b32_e32 v0, 15, v0
	s_lshl_b32 s12, s82, 11
	s_lshl_b32 s13, s84, 11
	s_lshl_b32 s3, s3, 9
	v_lshlrev_b32_e32 v0, 3, v0
	v_mov_b32_e32 v3, 0
	v_lshlrev_b32_e32 v1, 2, v14
	s_sub_i32 s22, s12, s13
	s_mov_b64 s[12:13], 0
	s_movk_i32 s23, 0x3c0
	s_mov_b64 s[16:17], 0x100000
	s_mov_b32 s24, 0x300000
	s_mov_b64 s[18:19], 0x400
	s_mov_b32 s25, 0x7ffff
	v_mov_b32_e32 v4, v14
	s_waitcnt lgkmcnt(0)
	v_lshrrev_b32_e32 v0, 6, v188
	s_sub_i32 s16, s2, s84
	s_lshl_b32 s16, s16, 3
	v_readfirstlane_b32 s17, v0
	v_and_b32_e32 v1, 15, v188
	v_bfe_u32 v2, v188, 4, 2
	s_add_i32 s16, s16, s17
	s_sub_i32 s18, s82, s84
	s_lshl_b32 s18, s18, 3
	v_lshlrev_b32_e32 v7, 8, v1
	v_lshl_add_u32 v7, v2, 6, v7
	v_lshlrev_b32_e32 v8, 7, v2
	v_lshlrev_b32_e32 v9, 11, v2
	v_lshl_add_u32 v9, v1, 3, v9
	v_lshlrev_b32_e32 v10, 8, v2
	v_lshl_add_u32 v10, v1, 2, v10
	s_cmp_lt_u32 s16, 0x800
	s_cbranch_scc0 .Lkc_done
.Lkc_tile:
	s_lshr_b32 s19, s16, 5
	s_bfe_u32 s20, s16, 0x10004
	s_and_b32 s21, s16, 15
	s_lshl_b32 s22, s20, 6
	s_add_i32 s22, s22, s19
	s_lshl_b32 s22, s22, 12
	v_add_u32_e32 v3, s22, v7
	global_load_dwordx4 v[16:19], v3, s[6:7] offset:0
	global_load_dwordx4 v[20:23], v3, s[6:7] offset:16
	global_load_dwordx4 v[24:27], v3, s[6:7] offset:32
	global_load_dwordx4 v[28:31], v3, s[6:7] offset:48
	global_load_dwordx4 v[32:35], v3, s[8:9] offset:0
	global_load_dwordx4 v[36:39], v3, s[8:9] offset:16
	global_load_dwordx4 v[40:43], v3, s[8:9] offset:32
	global_load_dwordx4 v[44:47], v3, s[8:9] offset:48
	s_lshl_b32 s23, s19, 1
	s_add_i32 s23, s23, s20
	s_mul_i32 s24, s23, 17
	s_add_i32 s24, s24, s21
	s_lshl_b32 s24, s24, 9
	s_add_i32 s24, s24, 0x100000
	v_add_u32_e32 v4, s24, v8
	global_load_dwordx4 v[48:51], v4, s[14:15] offset:0
	global_load_dwordx4 v[52:55], v4, s[14:15] offset:16
	global_load_dwordx4 v[56:59], v4, s[14:15] offset:32
	global_load_dwordx4 v[60:63], v4, s[14:15] offset:48
	global_load_dwordx4 v[64:67], v4, s[14:15] offset:64
	global_load_dwordx4 v[68:71], v4, s[14:15] offset:80
	global_load_dwordx4 v[72:75], v4, s[14:15] offset:96
	global_load_dwordx4 v[76:79], v4, s[14:15] offset:112
	s_lshl_b32 s25, s23, 13
	s_add_i32 s25, s25, 0x300000
	v_add_u32_e32 v5, s25, v9
	global_load_dwordx2 v[80:81], v5, s[14:15] offset:0
	global_load_dwordx2 v[82:83], v5, s[14:15] offset:128
	global_load_dwordx2 v[84:85], v5, s[14:15] offset:256
	global_load_dwordx2 v[86:87], v5, s[14:15] offset:384
	global_load_dwordx2 v[88:89], v5, s[14:15] offset:512
	global_load_dwordx2 v[90:91], v5, s[14:15] offset:640
	global_load_dwordx2 v[92:93], v5, s[14:15] offset:768
	global_load_dwordx2 v[94:95], v5, s[14:15] offset:896
	global_load_dwordx2 v[96:97], v5, s[14:15] offset:1024
	global_load_dwordx2 v[98:99], v5, s[14:15] offset:1152
	global_load_dwordx2 v[100:101], v5, s[14:15] offset:1280
	global_load_dwordx2 v[102:103], v5, s[14:15] offset:1408
	global_load_dwordx2 v[104:105], v5, s[14:15] offset:1536
	global_load_dwordx2 v[106:107], v5, s[14:15] offset:1664
	global_load_dwordx2 v[108:109], v5, s[14:15] offset:1792
	global_load_dwordx2 v[110:111], v5, s[14:15] offset:1920
	v_mov_b32_e32 v112, 0
	v_mov_b32_e32 v113, 0
	v_mov_b32_e32 v114, 0
	v_mov_b32_e32 v115, 0
	v_mov_b32_e32 v116, 0
	v_mov_b32_e32 v117, 0
	v_mov_b32_e32 v118, 0
	v_mov_b32_e32 v119, 0
	s_waitcnt vmcnt(0)
; __device__ __forceinline__ void p0b_tables(Frame& F, const Args& A, int t0) {
;     ...
;     for (int i = tg; i < 64 * 2 * 16 * 256; i += tn) {
;         const int c = i & 15, cp = (i >> 4) & 15, k = (i >> 8) & 15, dir = (i >> 12) & 1, g = i >> 13;
;         const f32x2* ap = apow + ((g * 2 + dir) * 17 + k) * 64; const f32x2* bb = bbar + (size_t)((g * 2 + dir) * 64) * 16 + c;
;         const float* cr = Cre + ((size_t)(dir * 64 + g) * 16 + cp) * 64; const float* ci = Cim + ((size_t)(dir * 64 + g) * 16 + cp) * 64;
;         float s = 0.f;
;         for (int p = 0; p < 64; ++p) { const f32x2 a = ap[p], b = bb[p * 16]; const float xr = a.x * b.x - a.y * b.y, xi = a.x * b.y + a.y * b.x; s += cr[p] * xr - ci[p] * xi; }
;         Kc[i] = s;
;     }
;     for (int i = tg; i < 64 * 256 * 32; i += tn) {
	v_mul_f32_e32 v120, v49, v81
	v_mul_f32_e32 v121, v49, v80
	v_fma_f32 v120, v48, v80, -v120
	v_fma_f32 v121, -v48, v81, -v121
	s_nop 1
	v_mfma_f32_16x16x4_f32 v[112:115], v16, v120, v[112:115]
	v_mfma_f32_16x16x4_f32 v[116:119], v32, v121, v[116:119]
	v_mul_f32_e32 v122, v51, v83
	v_mul_f32_e32 v123, v51, v82
	v_fma_f32 v122, v50, v82, -v122
	v_fma_f32 v123, -v50, v83, -v123
	s_nop 1
	v_mfma_f32_16x16x4_f32 v[112:115], v17, v122, v[112:115]
	v_mfma_f32_16x16x4_f32 v[116:119], v33, v123, v[116:119]
	v_mul_f32_e32 v120, v53, v85
	v_mul_f32_e32 v121, v53, v84
	v_fma_f32 v120, v52, v84, -v120
	v_fma_f32 v121, -v52, v85, -v121
	s_nop 1
	v_mfma_f32_16x16x4_f32 v[112:115], v18, v120, v[112:115]
	v_mfma_f32_16x16x4_f32 v[116:119], v34, v121, v[116:119]
	v_mul_f32_e32 v122, v55, v87
	v_mul_f32_e32 v123, v55, v86
	v_fma_f32 v122, v54, v86, -v122
	v_fma_f32 v123, -v54, v87, -v123
	s_nop 1
	v_mfma_f32_16x16x4_f32 v[112:115], v19, v122, v[112:115]
	v_mfma_f32_16x16x4_f32 v[116:119], v35, v123, v[116:119]
	v_mul_f32_e32 v120, v57, v89
	v_mul_f32_e32 v121, v57, v88
	v_fma_f32 v120, v56, v88, -v120
	v_fma_f32 v121, -v56, v89, -v121
	s_nop 1
	v_mfma_f32_16x16x4_f32 v[112:115], v20, v120, v[112:115]
	v_mfma_f32_16x16x4_f32 v[116:119], v36, v121, v[116:119]
	v_mul_f32_e32 v122, v59, v91
	v_mul_f32_e32 v123, v59, v90
	v_fma_f32 v122, v58, v90, -v122
	v_fma_f32 v123, -v58, v91, -v123
	s_nop 1
	v_mfma_f32_16x16x4_f32 v[112:115], v21, v122, v[112:115]
	v_mfma_f32_16x16x4_f32 v[116:119], v37, v123, v[116:119]
	v_mul_f32_e32 v120, v61, v93
	v_mul_f32_e32 v121, v61, v92
	v_fma_f32 v120, v60, v92, -v120
	v_fma_f32 v121, -v60, v93, -v121
	s_nop 1
	v_mfma_f32_16x16x4_f32 v[112:115], v22, v120, v[112:115]
	v_mfma_f32_16x16x4_f32 v[116:119], v38, v121, v[116:119]
	v_mul_f32_e32 v122, v63, v95
	v_mul_f32_e32 v123, v63, v94
	v_fma_f32 v122, v62, v94, -v122
	v_fma_f32 v123, -v62, v95, -v123
	s_nop 1
	v_mfma_f32_16x16x4_f32 v[112:115], v23, v122, v[112:115]
	v_mfma_f32_16x16x4_f32 v[116:119], v39, v123, v[116:119]
	v_mul_f32_e32 v120, v65, v97
	v_mul_f32_e32 v121, v65, v96
	v_fma_f32 v120, v64, v96, -v120
	v_fma_f32 v121, -v64, v97, -v121
	s_nop 1
	v_mfma_f32_16x16x4_f32 v[112:115], v24, v120, v[112:115]
	v_mfma_f32_16x16x4_f32 v[116:119], v40, v121, v[116:119]
	v_mul_f32_e32 v122, v67, v99
	v_mul_f32_e32 v123, v67, v98
	v_fma_f32 v122, v66, v98, -v122
	v_fma_f32 v123, -v66, v99, -v123
	s_nop 1
	v_mfma_f32_16x16x4_f32 v[112:115], v25, v122, v[112:115]
	v_mfma_f32_16x16x4_f32 v[116:119], v41, v123, v[116:119]
	v_mul_f32_e32 v120, v69, v101
	v_mul_f32_e32 v121, v69, v100
	v_fma_f32 v120, v68, v100, -v120
	v_fma_f32 v121, -v68, v101, -v121
	s_nop 1
	v_mfma_f32_16x16x4_f32 v[112:115], v26, v120, v[112:115]
	v_mfma_f32_16x16x4_f32 v[116:119], v42, v121, v[116:119]
	v_mul_f32_e32 v122, v71, v103
	v_mul_f32_e32 v123, v71, v102
	v_fma_f32 v122, v70, v102, -v122
	v_fma_f32 v123, -v70, v103, -v123
	s_nop 1
	v_mfma_f32_16x16x4_f32 v[112:115], v27, v122, v[112:115]
	v_mfma_f32_16x16x4_f32 v[116:119], v43, v123, v[116:119]
	v_mul_f32_e32 v120, v73, v105
	v_mul_f32_e32 v121, v73, v104
	v_fma_f32 v120, v72, v104, -v120
	v_fma_f32 v121, -v72, v105, -v121
	s_nop 1
	v_mfma_f32_16x16x4_f32 v[112:115], v28, v120, v[112:115]
	v_mfma_f32_16x16x4_f32 v[116:119], v44, v121, v[116:119]
	v_mul_f32_e32 v122, v75, v107
	v_mul_f32_e32 v123, v75, v106
	v_fma_f32 v122, v74, v106, -v122
	v_fma_f32 v123, -v74, v107, -v123
	s_nop 1
	v_mfma_f32_16x16x4_f32 v[112:115], v29, v122, v[112:115]
	v_mfma_f32_16x16x4_f32 v[116:119], v45, v123, v[116:119]
	v_mul_f32_e32 v120, v77, v109
	v_mul_f32_e32 v121, v77, v108
	v_fma_f32 v120, v76, v108, -v120
	v_fma_f32 v121, -v76, v109, -v121
	s_nop 1
	v_mfma_f32_16x16x4_f32 v[112:115], v30, v120, v[112:115]
	v_mfma_f32_16x16x4_f32 v[116:119], v46, v121, v[116:119]
	v_mul_f32_e32 v122, v79, v111
	v_mul_f32_e32 v123, v79, v110
	v_fma_f32 v122, v78, v110, -v122
	v_fma_f32 v123, -v78, v111, -v123
	s_nop 1
	v_mfma_f32_16x16x4_f32 v[112:115], v31, v122, v[112:115]
	v_mfma_f32_16x16x4_f32 v[116:119], v47, v123, v[116:119]
	s_lshl_b32 s24, s16, 10
	v_add_u32_e32 v6, s24, v10
	s_nop 7
	s_nop 3
	v_add_f32_e32 v112, v112, v116
	v_add_f32_e32 v113, v113, v117
	v_add_f32_e32 v114, v114, v118
	v_add_f32_e32 v115, v115, v119
	global_store_dword v6, v112, s[10:11] offset:0
	global_store_dword v6, v113, s[10:11] offset:64
	global_store_dword v6, v114, s[10:11] offset:128
	global_store_dword v6, v115, s[10:11] offset:192
	s_add_i32 s16, s16, s18
	s_cmp_lt_u32 s16, 0x800
	s_cbranch_scc1 .Lkc_tile
.Lkc_done:
	s_or_b64 exec, exec, s[12:13]
	s_add_u32 s10, s14, 0x100000
	s_addc_u32 s11, s15, 0
	s_add_u32 s12, s14, 0x300000
	s_addc_u32 s13, s15, 0
	s_add_u32 s16, s14, 0x900000
	s_addc_u32 s17, s15, 0
	v_lshlrev_b32_e32 v2, 3, v14
	s_lshl_b32 s18, s82, 12
	s_lshl_b32 s19, s84, 12
	s_sub_i32 s20, s18, s19
	s_mov_b64 s[18:19], 0
	s_movk_i32 s21, 0x80
	v_mov_b32_e32 v1, 0
	s_mov_b32 s22, 0x7ffff
	v_mov_b32_e32 v3, v2
	v_mov_b32_e32 v4, v14
